# attention loop: next half's K/V tile global loads issued inside the preceding sum chain (right after the LDS stores)
# speedup vs baseline: 1.0014x; 1.0014x over previous
.LBB0_836:
	s_add_i32 s88, s89, 2
	s_cmp_lt_u32 s88, s84
	s_cbranch_scc0 .Lq1_last
	global_load_dwordx4 v[28:31], v202, s[100:101] offset:-128
	global_load_dwordx4 v[32:35], v202, s[100:101]
	global_load_dwordx4 v[4:7], v203, s[100:101] offset:-128
	global_load_dwordx4 v[12:15], v203, s[100:101]
.Lq1_body:
	ds_read_b128 v[44:47], v214 offset:35840
	ds_read_b128 v[72:75], v214 offset:35904
	ds_read_b128 v[92:95], v214 offset:40192
	ds_read_b128 v[112:115], v214 offset:40256
	ds_read_b128 v[132:135], v214 offset:44544
	ds_read_b128 v[148:151], v214 offset:44608
	ds_read_b128 v[136:139], v214 offset:48896
	ds_read_b128 v[152:155], v214 offset:48960
	s_waitcnt lgkmcnt(7)
	v_mfma_f32_16x16x32_bf16 v[140:143], v[44:47], v[8:11], 0
	v_mfma_f32_16x16x32_bf16 v[44:47], v[44:47], v[20:23], 0
	s_waitcnt lgkmcnt(1)
	v_mfma_f32_16x16x32_bf16 v[156:159], v[92:95], v[8:11], 0
	v_mfma_f32_16x16x32_bf16 v[92:95], v[92:95], v[20:23], 0
	v_mfma_f32_16x16x32_bf16 v[160:163], v[132:135], v[8:11], 0
	v_mfma_f32_16x16x32_bf16 v[132:135], v[132:135], v[20:23], 0
	v_mfma_f32_16x16x32_bf16 v[164:167], v[136:139], v[8:11], 0
	v_mfma_f32_16x16x32_bf16 v[168:171], v[136:139], v[20:23], 0
	v_mfma_f32_16x16x32_bf16 v[144:147], v[72:75], v[16:19], v[140:143]
	v_mfma_f32_16x16x32_bf16 v[136:139], v[72:75], v[24:27], v[44:47]
	v_mfma_f32_16x16x32_bf16 v[44:47], v[112:115], v[16:19], v[156:159]
	v_mfma_f32_16x16x32_bf16 v[92:95], v[112:115], v[24:27], v[92:95]
	v_mfma_f32_16x16x32_bf16 v[140:143], v[148:151], v[16:19], v[160:163]
	v_mfma_f32_16x16x32_bf16 v[132:135], v[148:151], v[24:27], v[132:135]
	s_waitcnt lgkmcnt(0)
	v_mfma_f32_16x16x32_bf16 v[72:75], v[152:155], v[16:19], v[164:167]
	v_mfma_f32_16x16x32_bf16 v[112:115], v[152:155], v[24:27], v[168:171]
	s_cmp_eq_u32 s98, 0
	s_cbranch_scc1 .LBB0_859
	v_sub_f32_e32 v147, v147, v196
	v_sub_f32_e32 v146, v146, v196
	v_sub_f32_e32 v145, v145, v196
	v_sub_f32_e32 v144, v144, v196
	v_sub_f32_e32 v47, v47, v196
	v_sub_f32_e32 v46, v46, v196
	v_sub_f32_e32 v45, v45, v196
	v_sub_f32_e32 v44, v44, v196
	v_sub_f32_e32 v143, v143, v196
	v_sub_f32_e32 v142, v142, v196
	v_sub_f32_e32 v141, v141, v196
	v_sub_f32_e32 v140, v140, v196
	v_sub_f32_e32 v75, v75, v196
	v_sub_f32_e32 v74, v74, v196
	v_sub_f32_e32 v73, v73, v196
	v_sub_f32_e32 v72, v72, v196
	v_sub_f32_e32 v139, v139, v197
	v_sub_f32_e32 v138, v138, v197
	v_sub_f32_e32 v137, v137, v197
	v_sub_f32_e32 v136, v136, v197
	v_sub_f32_e32 v95, v95, v197
	v_sub_f32_e32 v94, v94, v197
	v_sub_f32_e32 v93, v93, v197
	v_sub_f32_e32 v92, v92, v197
	v_sub_f32_e32 v135, v135, v197
	v_sub_f32_e32 v134, v134, v197
	v_sub_f32_e32 v133, v133, v197
	v_sub_f32_e32 v132, v132, v197
	v_sub_f32_e32 v115, v115, v197
	v_sub_f32_e32 v114, v114, v197
	v_sub_f32_e32 v113, v113, v197
	v_sub_f32_e32 v112, v112, v197

.LBB0_865:
	v_pk_add_f32 v[2:3], v[198:199], v[2:3]
	s_waitcnt vmcnt(0)
	v_pk_add_f32 v[2:3], v[222:223], v[2:3]
	ds_write_b128 v211, v[28:31]
	v_pk_add_f32 v[2:3], v[224:225], v[2:3]
	ds_write_b128 v211, v[32:35] offset:128
	v_pk_add_f32 v[2:3], v[122:123], v[2:3]
	ds_write_b128 v213, v[4:7] offset:53248
	v_pk_add_f32 v[2:3], v[226:227], v[2:3]
	ds_write_b128 v213, v[12:15] offset:53376
	v_pk_add_f32 v[2:3], v[110:111], v[2:3]
	s_add_u32 s100, s100, 0x4000
	v_pk_add_f32 v[2:3], v[228:229], v[2:3]
	s_addc_u32 s101, s101, 0
	v_pk_add_f32 v[2:3], v[100:101], v[2:3]
	s_cmp_lt_u32 s89, s82
	s_cbranch_scc0 .Lq1_c1_nok
	global_load_dwordx4 v[28:31], v202, s[100:101] offset:-128
	global_load_dwordx4 v[32:35], v202, s[100:101]
.Lq1_c1_nok:
	v_pk_add_f32 v[2:3], v[96:97], v[2:3]
	global_load_dwordx4 v[4:7], v203, s[100:101] offset:-128
	v_pk_add_f32 v[2:3], v[230:231], v[2:3]
	global_load_dwordx4 v[12:15], v203, s[100:101]
	v_pk_add_f32 v[2:3], v[232:233], v[2:3]
	v_cvt_pk_bf16_f32 v112, v97, v231
	v_pk_add_f32 v[2:3], v[78:79], v[2:3]
	v_cvt_pk_bf16_f32 v113, v233, v79
	v_pk_add_f32 v[2:3], v[234:235], v[2:3]
	v_cvt_pk_bf16_f32 v114, v235, v67
	v_pk_add_f32 v[2:3], v[66:67], v[2:3]
	v_cvt_pk_bf16_f32 v115, v237, v55
	v_pk_add_f32 v[2:3], v[236:237], v[2:3]
	s_nop 0
	v_pk_add_f32 v[198:199], v[54:55], v[2:3]
.LBB0_866:
	s_waitcnt lgkmcnt(0)
	s_barrier
	s_cmp_ge_u32 s89, s83
	s_cbranch_scc1 .Lq1_h2_pvonly
	ds_read_b128 v[36:39], v214
	ds_read_b128 v[40:43], v214 offset:64
	ds_read_b128 v[60:63], v214 offset:4352
	ds_read_b128 v[84:87], v214 offset:4416
	ds_read_b128 v[64:67], v214 offset:8704
	ds_read_b128 v[124:127], v214 offset:8768
	ds_read_b128 v[108:111], v214 offset:13056
	ds_read_b128 v[100:103], v214 offset:13120
	s_waitcnt lgkmcnt(7)
	v_mfma_f32_16x16x32_bf16 v[120:123], v[36:39], v[8:11], 0
	v_mfma_f32_16x16x32_bf16 v[36:39], v[36:39], v[20:23], 0
	s_waitcnt lgkmcnt(1)
	v_mfma_f32_16x16x32_bf16 v[116:119], v[60:63], v[8:11], 0
	v_mfma_f32_16x16x32_bf16 v[60:63], v[60:63], v[20:23], 0
	v_mfma_f32_16x16x32_bf16 v[96:99], v[64:67], v[8:11], 0
	v_mfma_f32_16x16x32_bf16 v[64:67], v[64:67], v[20:23], 0
	v_mfma_f32_16x16x32_bf16 v[104:107], v[108:111], v[8:11], 0
	v_mfma_f32_16x16x32_bf16 v[76:79], v[108:111], v[20:23], 0
	v_mfma_f32_16x16x32_bf16 v[128:131], v[40:43], v[16:19], v[120:123]
	v_mfma_f32_16x16x32_bf16 v[108:111], v[40:43], v[24:27], v[36:39]
	v_mfma_f32_16x16x32_bf16 v[36:39], v[84:87], v[16:19], v[116:119]
	v_mfma_f32_16x16x32_bf16 v[60:63], v[84:87], v[24:27], v[60:63]
	v_mfma_f32_16x16x32_bf16 v[120:123], v[124:127], v[16:19], v[96:99]
	v_mfma_f32_16x16x32_bf16 v[64:67], v[124:127], v[24:27], v[64:67]
	s_waitcnt lgkmcnt(0)
	v_mfma_f32_16x16x32_bf16 v[40:43], v[100:103], v[16:19], v[104:107]
	v_mfma_f32_16x16x32_bf16 v[84:87], v[100:103], v[24:27], v[76:79]
	s_cmp_eq_u32 s98, 0
	s_cbranch_scc1 .LBB0_875
	v_sub_f32_e32 v131, v131, v196
	v_sub_f32_e32 v130, v130, v196
	v_sub_f32_e32 v129, v129, v196
	v_sub_f32_e32 v128, v128, v196
	v_sub_f32_e32 v39, v39, v196
	v_sub_f32_e32 v38, v38, v196
	v_sub_f32_e32 v37, v37, v196
	v_sub_f32_e32 v36, v36, v196
	v_sub_f32_e32 v123, v123, v196
	v_sub_f32_e32 v122, v122, v196
	v_sub_f32_e32 v121, v121, v196
	v_sub_f32_e32 v120, v120, v196
	v_sub_f32_e32 v43, v43, v196
	v_sub_f32_e32 v42, v42, v196
	v_sub_f32_e32 v41, v41, v196
	v_sub_f32_e32 v40, v40, v196
	v_sub_f32_e32 v111, v111, v197
	v_sub_f32_e32 v110, v110, v197
	v_sub_f32_e32 v109, v109, v197
	v_sub_f32_e32 v108, v108, v197
	v_sub_f32_e32 v63, v63, v197
	v_sub_f32_e32 v62, v62, v197
	v_sub_f32_e32 v61, v61, v197
	v_sub_f32_e32 v60, v60, v197
	v_sub_f32_e32 v67, v67, v197
	v_sub_f32_e32 v66, v66, v197
	v_sub_f32_e32 v65, v65, v197
	v_sub_f32_e32 v64, v64, v197
	v_sub_f32_e32 v87, v87, v197
	v_sub_f32_e32 v86, v86, v197
	v_sub_f32_e32 v85, v85, v197
	v_sub_f32_e32 v84, v84, v197

.LBB0_881:
	v_pk_add_f32 v[2:3], v[198:199], v[2:3]
	s_waitcnt vmcnt(0)
	v_pk_add_f32 v[2:3], v[222:223], v[2:3]
	ds_write_b128 v211, v[28:31] offset:35840
	v_pk_add_f32 v[2:3], v[224:225], v[2:3]
	ds_write_b128 v211, v[32:35] offset:35968
	v_pk_add_f32 v[2:3], v[142:143], v[2:3]
	ds_write_b128 v213, v[4:7] offset:17408
	v_pk_add_f32 v[2:3], v[226:227], v[2:3]
	ds_write_b128 v213, v[12:15] offset:17536
	v_pk_add_f32 v[2:3], v[138:139], v[2:3]
	s_add_u32 s100, s100, 0x4000
	v_pk_add_f32 v[2:3], v[228:229], v[2:3]
	s_addc_u32 s101, s101, 0
	v_pk_add_f32 v[2:3], v[154:155], v[2:3]
	s_addk_i32 s87, 0x80
	v_pk_add_f32 v[2:3], v[160:161], v[2:3]
	s_mov_b32 s89, s88
	v_pk_add_f32 v[2:3], v[230:231], v[2:3]
	s_add_i32 s88, s88, 2
	v_pk_add_f32 v[2:3], v[232:233], v[2:3]
	s_cmp_lt_u32 s88, s84
	s_cbranch_scc0 .Lq1_c2_skip
	global_load_dwordx4 v[28:31], v202, s[100:101] offset:-128
	global_load_dwordx4 v[32:35], v202, s[100:101]
	global_load_dwordx4 v[4:7], v203, s[100:101] offset:-128
	global_load_dwordx4 v[12:15], v203, s[100:101]
.Lq1_c2_skip:
	v_pk_add_f32 v[2:3], v[170:171], v[2:3]
	v_cvt_pk_bf16_f32 v84, v161, v231
	v_pk_add_f32 v[2:3], v[234:235], v[2:3]
	v_cvt_pk_bf16_f32 v85, v233, v171
	v_pk_add_f32 v[2:3], v[134:135], v[2:3]
	v_cvt_pk_bf16_f32 v86, v235, v135
	v_pk_add_f32 v[2:3], v[236:237], v[2:3]
	v_cvt_pk_bf16_f32 v87, v237, v183
	v_pk_add_f32 v[198:199], v[182:183], v[2:3]

.Lq1_h2_pvonly:
	ds_read_b64_tr_b16 v[64:65], v215 offset:53248
	ds_read_b64_tr_b16 v[108:109], v215 offset:53280
	ds_read_b64_tr_b16 v[120:121], v215 offset:53312
	ds_read_b64_tr_b16 v[128:129], v215 offset:53344
	ds_read_b64_tr_b16 v[66:67], v215 offset:57856
	ds_read_b64_tr_b16 v[110:111], v215 offset:57888
	ds_read_b64_tr_b16 v[122:123], v215 offset:57920
	ds_read_b64_tr_b16 v[130:131], v215 offset:57952
	s_waitcnt lgkmcnt(3)
	v_mfma_f32_16x16x32_bf16 v[124:127], v[44:47], v[64:67], v[144:147]
	v_mfma_f32_16x16x32_bf16 v[64:67], v[92:95], v[64:67], v[140:143]
	s_waitcnt lgkmcnt(2)
	v_mfma_f32_16x16x32_bf16 v[100:103], v[44:47], v[108:111], v[148:151]
	v_mfma_f32_16x16x32_bf16 v[108:111], v[92:95], v[108:111], v[136:139]
	s_waitcnt lgkmcnt(1)
	v_mfma_f32_16x16x32_bf16 v[116:119], v[44:47], v[120:123], v[156:159]
	v_mfma_f32_16x16x32_bf16 v[96:99], v[92:95], v[120:123], v[152:155]
	s_waitcnt lgkmcnt(0)
	v_mfma_f32_16x16x32_bf16 v[104:107], v[44:47], v[128:131], v[164:167]
	v_mfma_f32_16x16x32_bf16 v[76:79], v[92:95], v[128:131], v[160:163]
	ds_read_b64_tr_b16 v[120:121], v215 offset:53376
	ds_read_b64_tr_b16 v[128:129], v215 offset:53408
	ds_read_b64_tr_b16 v[88:89], v215 offset:53440
	ds_read_b64_tr_b16 v[80:81], v215 offset:53472
	ds_read_b64_tr_b16 v[122:123], v215 offset:57984
	ds_read_b64_tr_b16 v[130:131], v215 offset:58016
	ds_read_b64_tr_b16 v[90:91], v215 offset:58048
	ds_read_b64_tr_b16 v[82:83], v215 offset:58080
	s_waitcnt lgkmcnt(3)
	v_mfma_f32_16x16x32_bf16 v[52:55], v[44:47], v[120:123], v[172:175]
	v_mfma_f32_16x16x32_bf16 v[68:71], v[92:95], v[120:123], v[168:171]
	s_waitcnt lgkmcnt(2)
	v_mfma_f32_16x16x32_bf16 v[48:51], v[44:47], v[128:131], v[176:179]
	v_mfma_f32_16x16x32_bf16 v[56:59], v[92:95], v[128:131], v[132:135]
	s_waitcnt lgkmcnt(1)
	v_mfma_f32_16x16x32_bf16 v[218:221], v[44:47], v[88:91], v[184:187]
	v_mfma_f32_16x16x32_bf16 v[222:225], v[92:95], v[88:91], v[180:183]
	s_waitcnt lgkmcnt(0)
	v_mfma_f32_16x16x32_bf16 v[226:229], v[44:47], v[80:83], v[192:195]
	v_mfma_f32_16x16x32_bf16 v[230:233], v[92:95], v[80:83], v[188:191]
	ds_read_b64_tr_b16 v[120:121], v215 offset:62464
	ds_read_b64_tr_b16 v[88:89], v215 offset:62496
	ds_read_b64_tr_b16 v[80:81], v215 offset:62528
	ds_read_b64_tr_b16 v[234:235], v215 offset:62560
	ds_read_b64_tr_b16 v[122:123], v216 offset:13824
	ds_read_b64_tr_b16 v[90:91], v216 offset:13856
	ds_read_b64_tr_b16 v[82:83], v216 offset:13888
	ds_read_b64_tr_b16 v[236:237], v216 offset:13920
	s_waitcnt lgkmcnt(3)
	v_mfma_f32_16x16x32_bf16 v[128:131], v[72:75], v[120:123], v[124:127]
	v_mfma_f32_16x16x32_bf16 v[120:123], v[112:115], v[120:123], v[64:67]
	s_waitcnt lgkmcnt(2)
	v_mfma_f32_16x16x32_bf16 v[124:127], v[72:75], v[88:91], v[100:103]
	v_mfma_f32_16x16x32_bf16 v[108:111], v[112:115], v[88:91], v[108:111]
	s_waitcnt lgkmcnt(1)
	v_mfma_f32_16x16x32_bf16 v[116:119], v[72:75], v[80:83], v[116:119]
	v_mfma_f32_16x16x32_bf16 v[100:103], v[112:115], v[80:83], v[96:99]
	s_waitcnt lgkmcnt(0)
	v_mfma_f32_16x16x32_bf16 v[104:107], v[72:75], v[234:237], v[104:107]
	v_mfma_f32_16x16x32_bf16 v[96:99], v[112:115], v[234:237], v[76:79]
	ds_read_b64_tr_b16 v[64:65], v215 offset:62592
	ds_read_b64_tr_b16 v[234:235], v215 offset:62624
	ds_read_b64_tr_b16 v[238:239], v215 offset:62656
	ds_read_b64_tr_b16 v[242:243], v215 offset:62688
	ds_read_b64_tr_b16 v[66:67], v216 offset:13952
	ds_read_b64_tr_b16 v[236:237], v216 offset:13984
	ds_read_b64_tr_b16 v[240:241], v216 offset:14016
	ds_read_b64_tr_b16 v[244:245], v216 offset:14048
	s_waitcnt lgkmcnt(3)
	v_mfma_f32_16x16x32_bf16 v[88:91], v[72:75], v[64:67], v[52:55]
	v_mfma_f32_16x16x32_bf16 v[76:79], v[112:115], v[64:67], v[68:71]
	s_waitcnt lgkmcnt(2)
	v_mfma_f32_16x16x32_bf16 v[80:83], v[72:75], v[234:237], v[48:51]
	v_mfma_f32_16x16x32_bf16 v[64:67], v[112:115], v[234:237], v[56:59]
	s_waitcnt lgkmcnt(1)
	v_mfma_f32_16x16x32_bf16 v[68:71], v[72:75], v[238:241], v[218:221]
	v_mfma_f32_16x16x32_bf16 v[52:55], v[112:115], v[238:241], v[222:225]
	s_waitcnt lgkmcnt(0)
	v_mfma_f32_16x16x32_bf16 v[56:59], v[72:75], v[242:245], v[226:229]
	v_mfma_f32_16x16x32_bf16 v[48:51], v[112:115], v[242:245], v[230:233]
	s_mov_b64 s[2:3], 0
	s_waitcnt vmcnt(0)
	ds_write_b128 v211, v[28:31] offset:35840
	ds_write_b128 v211, v[32:35] offset:35968
	ds_write_b128 v213, v[4:7] offset:17408
	ds_write_b128 v213, v[12:15] offset:17536
	s_add_u32 s100, s100, 0x4000
	s_addc_u32 s101, s101, 0
	s_addk_i32 s87, 0x80
	s_mov_b32 s89, s88
	s_add_i32 s88, s88, 2
	s_cmp_lt_u32 s88, s84
	s_cbranch_scc0 .Lq1_c3_skip
	global_load_dwordx4 v[28:31], v202, s[100:101] offset:-128
	global_load_dwordx4 v[32:35], v202, s[100:101]
	global_load_dwordx4 v[4:7], v203, s[100:101] offset:-128
	global_load_dwordx4 v[12:15], v203, s[100:101]
.Lq1_c3_skip:
	s_branch .LBB0_882
